# row-wise phases: each workgroup now owns rows of batch blockIdx%8 (the batch its XCD produces/consumes in the GEMMs) instead of rows strided across all batches
# speedup vs baseline: 1.0019x; 1.0019x over previous
; #define TIDX tid_launder()
; #define LAS __attribute__((address_space(3)))
; __device__ __forceinline__ void rowwise(ArgsP a, LAS unsigned char* lds, const float* xin, const bf16_t* f, float alpha, const float* gpost, const float* gnext,
;                                         bool forget, const float* w_in_L, const float* fbias, bool final) {
;     const int tid = TIDX, lane = tid & 63, wave = __builtin_amdgcn_readfirstlane(tid >> 6);
;     LAS float* wf = (LAS float*)lds;
;     if (forget) {
;         for (int k = tid; k < DM; k += 512) { const float* src = w_in_L + (size_t)k * INW + 2816;
; #pragma unroll
;             for (int j = 0; j < 6; ++j) wf[j * DM + k] = src[j]; }
;         __syncthreads();
;     }
;     bf16_t* HB = (bf16_t*)(a->ws + WS_U);
;     float* R2 = (float*)(a->ws + WS_R2);
;     float* logf_out = (float*)(a->ws + WS_LOGF);
;     const int gw = blockIdx.x * 8 + wave, NGW = gridDim.x * 8;
;     if (xin) {
;         f32x4 xn[8];
;         { const f32x4* hp = (const f32x4*)(xin + (size_t)gw * DM) + lane;
; #pragma unroll
;           for (int j = 0; j < 8; ++j) xn[j] = hp[64 * j]; }
;         for (int r = gw; r < T_; r += NGW) {
; __device__ __forceinline__ void attn_phase(ArgsP a, LAS unsigned char* lds, int L) {
;     ...
;     const int blk = blockIdx.x, G = gridDim.x;
;     const int nrounds = (G == 256) ? 3 : (768 + G - 1) / G;
;     for (int r = 0; r < nrounds; ++r) {
;         const int e = (G == 256) ? ((r == 0) ? blk : (r == 1 ? 511 - blk : 512 + (blk ^ 1))) : (blk + r * G);
;         if (e >= 768) break;
;         const int qt = 7 - e / 96, rest = e % 96, moba = rest & 1, bh = rest >> 1;
.LBB0_13:
	s_mul_i32 s0, s27, s26
	s_lshl_b32 s11, s2, 3
	s_lshl_b32 s28, s26, 3
	s_lshl_b32 s27, s26, 4
	s_cmpk_lt_i32 s2, 0x200
	s_cselect_b64 s[4:5], -1, 0
	s_ashr_i32 s33, s2, 31
	s_lshr_b32 s1, s33, 29
	s_add_i32 s1, s2, s1
	s_ashr_i32 s3, s1, 3
	s_and_b32 s1, s1, -8
	v_writelane_b32 v255, s4, 4
	s_sub_i32 s1, s2, s1
	s_ashr_i32 s67, s26, 31
	v_writelane_b32 v255, s5, 5
	s_lshl_b32 s4, s1, 6
	s_cmpk_lg_i32 s26, 0x100
	s_cselect_b64 s[6:7], -1, 0
	v_writelane_b32 v255, s6, 6
	s_add_i32 s5, s26, 0x2ff
	s_movk_i32 s51, 0x161
	v_writelane_b32 v255, s7, 7
	s_sub_i32 s6, 0x1ff, s2
	v_writelane_b32 v255, s6, 8
	s_and_b32 s7, s2, 7
	s_lshl_b32 s7, s7, 11
	s_lshr_b32 s8, s2, 3
	s_lshl_b32 s8, s8, 3
	s_add_i32 s8, s8, s7
	v_writelane_b32 v255, s8, 62
	s_add_i32 s32, s7, 0x7ff
	s_lshr_b32 s7, s2, 5
	s_mov_b32 s6, s2
	s_cmp_eq_u32 s7, 1
	s_cselect_b32 s8, 0xa0, 0
	s_add_i32 s6, s6, s8
	s_cmp_eq_u32 s7, 6
	s_cselect_b32 s8, 0xa0, 0
	s_sub_i32 s6, s6, s8
	s_xor_b32 s6, s6, 1
	s_addk_i32 s6, 0x200
	s_cmpk_lt_i32 s2, 0x100
	v_writelane_b32 v255, s6, 9
	s_cselect_b64 s[6:7], -1, 0
	v_writelane_b32 v255, s6, 10
	s_cmpk_lt_i32 s2, 0x500
	v_lshrrev_b32_e32 v1, 20, v0
	v_writelane_b32 v255, s7, 11
	s_cselect_b64 s[6:7], -1, 0
	v_writelane_b32 v255, s6, 12
	s_cmp_lt_i32 s1, 0
	s_cselect_b32 s8, s51, 0x160
	v_writelane_b32 v255, s7, 13
	s_movk_i32 s7, 0xa1
	s_cselect_b32 s7, s7, 0xa0
	s_mul_i32 s6, s1, 0x41
	s_mul_i32 s7, s7, s1
	s_cselect_b32 s4, s6, s4
	s_add_i32 s7, s7, s3
	s_mul_hi_i32 s6, s7, 0x66666667
	s_lshr_b32 s9, s6, 31
	s_ashr_i32 s6, s6, 6
	s_add_i32 s6, s6, s9
	s_mul_i32 s9, s6, 0xa0
	s_sub_i32 s7, s7, s9
	s_bfe_u32 s9, s7, 0x3001c
	s_add_i32 s9, s7, s9
	s_sext_i32_i16 s10, s9
	s_and_b32 s9, s9, 0xfff8
	s_sub_i32 s7, s7, s9
	s_lshl_b32 s6, s6, 3
	s_sext_i32_i16 s7, s7
	s_add_i32 s6, s6, s7
	v_writelane_b32 v255, s6, 14
	s_ashr_i32 s6, s10, 3
	s_cmpk_lt_i32 s2, 0xb00
	v_writelane_b32 v255, s6, 15
	s_cselect_b64 s[6:7], -1, 0
	s_mul_i32 s1, s8, s1
	v_writelane_b32 v255, s6, 16
	s_add_i32 s1, s1, s3
	v_lshrrev_b32_e32 v0, 10, v0
	v_writelane_b32 v255, s7, 17
	s_mul_hi_i32 s6, s1, 0x2e8ba2e9
	s_lshr_b32 s7, s6, 31
	s_ashr_i32 s6, s6, 6
	s_add_i32 s6, s6, s7
	s_mul_i32 s7, s6, 0x160
	s_sub_i32 s1, s1, s7
	s_bfe_u32 s7, s1, 0x3001c
	s_add_i32 s7, s1, s7
	s_sext_i32_i16 s8, s7
	s_and_b32 s7, s7, 0xfff8
	s_sub_i32 s1, s1, s7
	s_lshl_b32 s6, s6, 3
	s_sext_i32_i16 s1, s1
	s_add_i32 s1, s6, s1
	v_writelane_b32 v255, s1, 18
	v_or_b32_e32 v0, v0, v1
	v_readlane_b32 s6, v255, 0
	v_readlane_b32 s7, v255, 1
	s_load_dword s1, s[6:7], 0xe0
	s_ashr_i32 s6, s8, 3
	v_writelane_b32 v255, s6, 19
	s_lshl_b32 s6, s2, 9
	v_writelane_b32 v255, s6, 20
	s_waitcnt lgkmcnt(0)
	s_mul_i32 s0, s0, s1
	v_writelane_b32 v255, s0, 21
	s_movk_i32 s0, 0x3ff
	v_and_or_b32 v1, v0, s0, v219
	s_add_i32 s0, s4, s3
	s_ashr_i32 s1, s0, 31
	s_lshr_b32 s1, s1, 27
	s_add_i32 s1, s0, s1
	s_ashr_i32 s3, s1, 5
	s_and_b32 s1, s1, 0xffe0
	s_sub_i32 s1, s0, s1
	s_bfe_i32 s0, s1, 0x80000
	s_bfe_u32 s0, s0, 0x2000d
	s_add_i32 s4, s1, s0
	s_bfe_i32 s0, s4, 0x80000
	s_and_b32 s4, s4, 0xfc
	s_sub_i32 s1, s1, s4
	s_abs_i32 s4, s26
	v_cvt_f32_u32_e32 v0, s4
	s_lshl_b32 s3, s3, 2
	s_sext_i32_i8 s1, s1
	s_sext_i32_i16 s6, s0
	v_rcp_iflag_f32_e32 v0, v0
	s_add_i32 s1, s3, s1
	s_lshr_b32 s0, s6, 2
	v_writelane_b32 v255, s1, 22
	v_mul_f32_e32 v0, 0x4f7ffffe, v0
	v_cvt_u32_f32_e32 v0, v0
	s_ashr_i32 s1, s6, 2
	v_writelane_b32 v255, s1, 23
	s_bfe_i64 s[0:1], s[0:1], 0x100000
	v_writelane_b32 v255, s0, 24
	s_sub_i32 s3, 0, s4
	s_lshl_b32 s40, s26, 9
	v_writelane_b32 v255, s1, 25
	s_xor_b32 s0, s5, s26
	s_abs_i32 s1, s5
	v_readfirstlane_b32 s5, v0
	s_mul_i32 s3, s3, s5
	s_mul_hi_u32 s3, s5, s3
	s_add_i32 s5, s5, s3
	s_mul_hi_u32 s3, s1, s5
	s_mul_i32 s5, s3, s4
	s_sub_i32 s1, s1, s5
	s_ashr_i32 s29, s28, 31
	s_ashr_i32 s0, s0, 31
	s_add_i32 s5, s3, 1
	s_sub_i32 s6, s1, s4
	s_cmp_ge_u32 s1, s4
	s_cselect_b32 s3, s5, s3
	s_cselect_b32 s1, s6, s1
	s_add_i32 s5, s3, 1
	s_cmp_ge_u32 s1, s4
	s_cselect_b32 s1, s5, s3
	s_xor_b32 s1, s1, s0
	s_sub_i32 s0, s1, s0
	v_writelane_b32 v255, s0, 26
	s_lshl_b32 s0, s2, 6
	v_writelane_b32 v255, s0, 27
	s_lshl_b32 s0, s26, 6
	v_writelane_b32 v255, s0, 28
	v_writelane_b32 v255, s11, 29
	s_add_i32 s0, s11, s28
	v_writelane_b32 v255, s0, 30
	s_add_i32 s0, 0, 0x19800
	v_writelane_b32 v255, s0, 31
	s_add_i32 s0, 0, 0x1aa24
	v_writelane_b32 v255, s0, 32
	s_add_i32 s0, 0, 0x1aa28
	v_writelane_b32 v255, s0, 33
	s_add_i32 s0, 0, 0x1aa2c
	v_writelane_b32 v255, s0, 34
	s_add_i32 s0, 0, 0x1aa30
	v_writelane_b32 v255, s0, 35
	s_add_i32 s0, 0, 0x1aa34
	v_writelane_b32 v255, s0, 36
	s_add_i32 s0, 0, 0x1aa38
	v_writelane_b32 v255, s0, 37
	s_add_i32 s0, 0, 0x1aa3c
	v_writelane_b32 v255, s0, 38
	s_add_i32 s0, 0, 0x1aa00
	v_writelane_b32 v255, s0, 39
	s_add_i32 s0, 0, 0x17900
	v_writelane_b32 v255, s0, 40
	s_add_i32 s0, 0, 0x11000
	v_writelane_b32 v255, s0, 41
	s_add_i32 s3, 0, 0x23fc0
	v_writelane_b32 v255, s3, 42
	s_add_i32 s3, 0, 0x23fc4
	v_writelane_b32 v255, s3, 43
	v_cmp_eq_u32_e64 s[4:5], 0, v219
	s_lshl_b64 s[46:47], s[28:29], 13
	v_mbcnt_lo_u32_b32 v2, -1, 0
	v_writelane_b32 v255, s4, 44
	s_mul_i32 s44, s26, 0x8400
	s_mul_hi_i32 s45, s28, 0x1080
	v_writelane_b32 v255, s5, 45
	v_cmp_eq_u32_e64 s[4:5], 0, v1
	s_movk_i32 s50, 0x2000
	s_movk_i32 s30, 0x840
	v_writelane_b32 v255, s4, 46
	v_mov_b32_e32 v0, 0
	v_mov_b32_e32 v224, 0x358637bd
	v_writelane_b32 v255, s5, 47
	v_writelane_b32 v255, s46, 48
	v_mov_b32_e32 v213, 1
	v_mov_b32_e32 v227, 0x1080
	v_mov_b32_e32 v228, 0x3a000000
	v_mbcnt_hi_u32_b32 v229, -1, v2
	v_mov_b32_e32 v16, 0xff800000
	v_mov_b32_e32 v230, 0x80
	s_mov_b32 s21, 0x800000
	s_movk_i32 s42, 0x2800
	s_movk_i32 s31, 0x110
	s_mov_b32 s69, 0xa0000
	s_mov_b32 s34, 0xff800000
	s_movk_i32 s0, 0x1640
	s_mov_b32 s1, 0xb0000
	s_movk_i32 s22, 0x2c80
	s_mov_b32 s3, s24
	s_mov_b64 s[48:49], 0x80
	s_lshl_b64 s[52:53], s[28:29], 2
	s_mov_b32 s55, 0
	s_mov_b64 s[56:57], 0x80000
	s_mov_b64 s[58:59], 0x90000
	s_mov_b64 s[60:61], 0xa0000
	s_mov_b64 s[62:63], 0xb0000
	s_mov_b32 s66, 0x3e0293ee
	v_writelane_b32 v255, s47, 49
	s_branch .LBB0_16

; __device__ __forceinline__ void rowwise(ArgsP a, LAS unsigned char* lds, const float* xin, const bf16_t* f, float alpha, const float* gpost, const float* gnext,
;                                         bool forget, const float* w_in_L, const float* fbias, bool final) {
;     ...
;     f32x4 gp[8], gn[8];
; #pragma unroll
;     for (int j = 0; j < 8; ++j) { gp[j] = ((const f32x4*)gpost)[64 * j + lane]; gn[j] = forget ? ((const f32x4*)gnext)[64 * j + lane] : (f32x4){0.f, 0.f, 0.f, 0.f}; }
;     u32x2 hn[8], fn[8], hn2[8], fn2[8]; float rn = R2[gw], rn2 = 1.f;
;     { const u32x2* hp = (const u32x2*)(HB + (size_t)gw * LDU) + lane; const u32x2* fp = (const u32x2*)(f + (size_t)gw * DM) + lane;
; #pragma unroll
;       for (int j = 0; j < 8; ++j) { hn[j] = hp[64 * j]; fn[j] = fp[64 * j]; } }
;     if (gw + NGW < T_) { rn2 = R2[gw + NGW]; const u32x2* hp = (const u32x2*)(HB + (size_t)(gw + NGW) * LDU) + lane; const u32x2* fp = (const u32x2*)(f + (size_t)(gw + NGW) * DM) + lane;
; #pragma unroll
;       for (int j = 0; j < 8; ++j) { hn2[j] = hp[64 * j]; fn2[j] = fp[64 * j]; } }
.LBB0_47:
	s_and_b64 vcc, exec, s[4:5]
	s_cbranch_vccz .LBB0_57
	s_load_dwordx2 s[4:5], s[72:73], 0x80
	v_readlane_b32 s6, v255, 50
	v_readlane_b32 s7, v255, 51
	s_lshl_b64 s[6:7], s[6:7], 2
	s_waitcnt vmcnt(0)
	v_mov_b32_e32 v1, v219
	s_waitcnt lgkmcnt(0)
	s_add_u32 s4, s4, s6
	v_readfirstlane_b32 s3, v1
	s_addc_u32 s5, s5, s7
	s_ashr_i32 s6, s3, 6
	v_and_b32_e32 v17, 63, v1
	s_add_u32 s3, s70, 0xb280000
	v_readlane_b32 s7, v255, 62
	s_addc_u32 s16, s71, 0
	s_add_i32 s8, s6, s7
	v_lshlrev_b32_e32 v14, 4, v17
	v_mov_b32_e32 v15, v0
	v_lshl_add_u64 v[22:23], s[4:5], 0, v[14:15]
	global_load_dwordx4 v[2:5], v14, s[4:5]
	global_load_dwordx4 v[6:9], v14, s[4:5] offset:1024
	global_load_dwordx4 v[10:13], v14, s[4:5] offset:2048
	global_load_dwordx4 v[18:21], v14, s[4:5] offset:3072
	s_movk_i32 s4, 0x1000
	s_ashr_i32 s9, s8, 31
	v_add_co_u32_e32 v14, vcc, s4, v22
	s_lshl_b64 s[4:5], s[8:9], 2
	s_add_u32 s4, s3, s4
	s_addc_u32 s5, s16, s5
	s_mul_i32 s6, s8, 0x1080
	s_mul_hi_i32 s7, s8, 0x1080
	s_add_u32 s6, s78, s6
	s_addc_u32 s7, s79, s7
	s_lshl_b64 s[14:15], s[8:9], 12
	v_addc_co_u32_e32 v15, vcc, 0, v23, vcc
	s_add_u32 s14, s80, s14
	global_load_dwordx4 v[22:25], v[14:15], off
	global_load_dwordx4 v[26:29], v[14:15], off offset:1024
	global_load_dwordx4 v[30:33], v[14:15], off offset:2048
	global_load_dwordx4 v[34:37], v[14:15], off offset:3072
	v_lshlrev_b32_e32 v70, 3, v17
	s_addc_u32 s15, s81, s15
	global_load_dword v136, v0, s[4:5]
	global_load_dwordx2 v[128:129], v70, s[6:7]
	global_load_dwordx2 v[126:127], v70, s[6:7] offset:512
	global_load_dwordx2 v[122:123], v70, s[6:7] offset:1024
	global_load_dwordx2 v[118:119], v70, s[6:7] offset:1536
	global_load_dwordx2 v[114:115], v70, s[6:7] offset:2048
	global_load_dwordx2 v[112:113], v70, s[6:7] offset:2560
	global_load_dwordx2 v[106:107], v70, s[6:7] offset:3072
	global_load_dwordx2 v[124:125], v70, s[14:15] offset:1536
	global_load_dwordx2 v[120:121], v70, s[14:15] offset:2048
	global_load_dwordx2 v[116:117], v70, s[14:15] offset:2560
	global_load_dwordx2 v[110:111], v70, s[14:15] offset:3072
	global_load_dwordx2 v[134:135], v70, s[14:15]
	global_load_dwordx2 v[132:133], v70, s[14:15] offset:512
	global_load_dwordx2 v[130:131], v70, s[14:15] offset:1024
	global_load_dwordx2 v[104:105], v70, s[6:7] offset:3584
	global_load_dwordx2 v[108:109], v70, s[14:15] offset:3584
	s_add_i32 s6, s8, 0x100
	s_cmp_gt_i32 s6, s32
	v_mov_b32_e32 v1, 1.0
	s_cbranch_scc1 .LBB0_50
	s_ashr_i32 s7, s6, 31
	s_add_u32 s4, s4, 0x400
	s_addc_u32 s5, s5, 0
	global_load_dword v1, v0, s[4:5]
	s_mul_i32 s4, s6, 0x1080
	s_mul_hi_i32 s5, s6, 0x1080
	s_add_u32 s4, s78, s4
	s_addc_u32 s5, s79, s5
	s_lshl_b64 s[6:7], s[6:7], 12
	s_add_u32 s6, s80, s6
	s_addc_u32 s7, s81, s7
	global_load_dwordx2 v[14:15], v70, s[4:5]
	global_load_dwordx2 v[42:43], v70, s[6:7]
	global_load_dwordx2 v[38:39], v70, s[4:5] offset:512
	global_load_dwordx2 v[46:47], v70, s[6:7] offset:512
	global_load_dwordx2 v[40:41], v70, s[4:5] offset:1024
	global_load_dwordx2 v[50:51], v70, s[6:7] offset:1024
	global_load_dwordx2 v[44:45], v70, s[4:5] offset:1536
	global_load_dwordx2 v[54:55], v70, s[6:7] offset:1536
	global_load_dwordx2 v[48:49], v70, s[4:5] offset:2048
	global_load_dwordx2 v[58:59], v70, s[6:7] offset:2048
	global_load_dwordx2 v[52:53], v70, s[4:5] offset:2560
	global_load_dwordx2 v[60:61], v70, s[6:7] offset:2560
	global_load_dwordx2 v[56:57], v70, s[4:5] offset:3072
	global_load_dwordx2 v[62:63], v70, s[6:7] offset:3072
	global_load_dwordx2 v[64:65], v70, s[4:5] offset:3584
	global_load_dwordx2 v[66:67], v70, s[6:7] offset:3584
.LBB0_50:
	s_cmp_gt_i32 s8, s32
	s_cbranch_scc1 .LBB0_57
	v_mov_b32_e32 v71, v0
	v_lshl_add_u64 v[68:69], s[78:79], 0, v[70:71]
	v_lshl_add_u64 v[70:71], s[80:81], 0, v[70:71]
	v_cmp_eq_u32_e64 s[6:7], 0, v17
	s_waitcnt vmcnt(16)
	v_mov_b32_e32 v17, v1
	s_waitcnt vmcnt(1)
	v_mov_b64_e32 v[86:87], v[64:65]
	v_mov_b64_e32 v[84:85], v[56:57]
	v_mov_b64_e32 v[82:83], v[52:53]
	v_mov_b64_e32 v[80:81], v[48:49]
	v_mov_b64_e32 v[78:79], v[44:45]
	v_mov_b64_e32 v[76:77], v[40:41]
	v_mov_b64_e32 v[74:75], v[38:39]
	v_mov_b64_e32 v[72:73], v[14:15]
	s_waitcnt vmcnt(0)
	v_mov_b64_e32 v[96:97], v[66:67]
	v_mov_b64_e32 v[98:99], v[62:63]
	v_mov_b64_e32 v[100:101], v[60:61]
	v_mov_b64_e32 v[102:103], v[58:59]
	v_mov_b64_e32 v[88:89], v[54:55]
	v_mov_b64_e32 v[90:91], v[50:51]
	v_mov_b64_e32 v[92:93], v[46:47]
	v_mov_b64_e32 v[94:95], v[42:43]
	s_branch .LBB0_53
; __device__ __forceinline__ unsigned cvtpk(float lo, float hi) { unsigned r; asm volatile("v_cvt_pk_bf16_f32 %0, %1, %2" : "=v"(r) : "v"(lo), "v"(hi)); return r; }
; __device__ __forceinline__ void rowwise(ArgsP a, LAS unsigned char* lds, const float* xin, const bf16_t* f, float alpha, const float* gpost, const float* gnext,
;                                         bool forget, const float* w_in_L, const float* fbias, bool final) {
;     ...
;         rn = rn2;
; #pragma unroll
;         for (int j = 0; j < 8; ++j) { hn[j] = hn2[j]; fn[j] = fn2[j]; }
;         if (r + 2 * NGW < T_) { rn2 = R2[r + 2 * NGW]; const u32x2* hp = (const u32x2*)(HB + (size_t)(r + 2 * NGW) * LDU) + lane; const u32x2* fp = (const u32x2*)(f + (size_t)(r + 2 * NGW) * DM) + lane;
; #pragma unroll
;             for (int j = 0; j < 8; ++j) { hn2[j] = hp[64 * j]; fn2[j] = fp[64 * j]; } }
;     ...
;             for (int j = 0; j < 8; ++j) { h[j] = h[j] * r2; u32x2 o; o.x = cvtpk(h[j].x, h[j].y); o.y = cvtpk(h[j].z, h[j].w); st8(hbp + 64 * j, o); }
.LBB0_52:
	s_or_b64 exec, exec, s[4:5]
	v_pk_mul_f32 v[106:107], v[106:107], v[136:137] op_sel_hi:[1,0]
	v_mad_i64_i32 v[138:139], s[4:5], s8, v227, v[68:69]
	v_pk_mul_f32 v[104:105], v[104:105], v[136:137] op_sel_hi:[1,0]
	v_cvt_pk_bf16_f32 v106, v106, v107
	s_sub_i32 s8, s14, 0x100
	v_cvt_pk_bf16_f32 v107, v104, v105
	global_store_dwordx2 v[138:139], v[106:107], off
	v_pk_mul_f32 v[106:107], v[110:111], v[136:137] op_sel_hi:[1,0]
	v_pk_mul_f32 v[104:105], v[108:109], v[136:137] op_sel_hi:[1,0]
	v_cvt_pk_bf16_f32 v106, v106, v107
	s_cmp_gt_i32 s8, s32
	v_cvt_pk_bf16_f32 v107, v104, v105
	global_store_dwordx2 v[138:139], v[106:107], off offset:512
	v_pk_mul_f32 v[106:107], v[116:117], v[136:137] op_sel_hi:[1,0]
	v_pk_mul_f32 v[104:105], v[112:113], v[136:137] op_sel_hi:[1,0]
	v_cvt_pk_bf16_f32 v106, v106, v107
	v_mov_b64_e32 v[112:113], v[52:53]
	v_cvt_pk_bf16_f32 v107, v104, v105
	global_store_dwordx2 v[138:139], v[106:107], off offset:1024
	v_pk_mul_f32 v[106:107], v[120:121], v[136:137] op_sel_hi:[1,0]
	v_pk_mul_f32 v[104:105], v[114:115], v[136:137] op_sel_hi:[1,0]
	v_cvt_pk_bf16_f32 v106, v106, v107
	v_mov_b64_e32 v[114:115], v[48:49]
	v_cvt_pk_bf16_f32 v107, v104, v105
	global_store_dwordx2 v[138:139], v[106:107], off offset:1536
	v_pk_mul_f32 v[106:107], v[118:119], v[136:137] op_sel_hi:[1,0]
	v_pk_mul_f32 v[104:105], v[124:125], v[136:137] op_sel_hi:[1,0]
	v_cvt_pk_bf16_f32 v106, v106, v107
	v_mov_b64_e32 v[118:119], v[44:45]
	v_cvt_pk_bf16_f32 v107, v104, v105
	global_store_dwordx2 v[138:139], v[106:107], off offset:2048
	v_pk_mul_f32 v[106:107], v[128:129], v[136:137] op_sel_hi:[1,0]
	v_pk_mul_f32 v[104:105], v[122:123], v[136:137] op_sel_hi:[1,0]
	v_cvt_pk_bf16_f32 v106, v106, v107
	v_mov_b64_e32 v[122:123], v[40:41]
	v_cvt_pk_bf16_f32 v107, v104, v105
	global_store_dwordx2 v[138:139], v[106:107], off offset:2560
	v_pk_mul_f32 v[106:107], v[132:133], v[136:137] op_sel_hi:[1,0]
	v_pk_mul_f32 v[104:105], v[126:127], v[136:137] op_sel_hi:[1,0]
	v_cvt_pk_bf16_f32 v106, v106, v107
	v_mov_b64_e32 v[126:127], v[38:39]
	v_cvt_pk_bf16_f32 v107, v104, v105
	global_store_dwordx2 v[138:139], v[106:107], off offset:3072
	v_pk_mul_f32 v[106:107], v[130:131], v[136:137] op_sel_hi:[1,0]
	v_pk_mul_f32 v[104:105], v[134:135], v[136:137] op_sel_hi:[1,0]
	v_cvt_pk_bf16_f32 v106, v106, v107
	v_mov_b64_e32 v[128:129], v[14:15]
	v_cvt_pk_bf16_f32 v107, v104, v105
	global_store_dwordx2 v[138:139], v[106:107], off offset:3584
	v_mov_b64_e32 v[104:105], v[64:65]
	v_mov_b64_e32 v[106:107], v[56:57]
	v_mov_b64_e32 v[108:109], v[66:67]
	v_mov_b64_e32 v[110:111], v[62:63]
	v_mov_b64_e32 v[116:117], v[60:61]
	v_mov_b64_e32 v[120:121], v[58:59]
	v_mov_b64_e32 v[124:125], v[54:55]
	v_mov_b64_e32 v[130:131], v[50:51]
	v_mov_b64_e32 v[132:133], v[46:47]
	v_mov_b64_e32 v[134:135], v[42:43]
	s_waitcnt vmcnt(12)
	v_mov_b64_e32 v[64:65], v[86:87]
	v_mov_b64_e32 v[56:57], v[84:85]
	v_mov_b64_e32 v[52:53], v[82:83]
	v_mov_b64_e32 v[48:49], v[80:81]
	v_mov_b64_e32 v[44:45], v[78:79]
	v_mov_b64_e32 v[40:41], v[76:77]
	v_mov_b64_e32 v[38:39], v[74:75]
	v_mov_b64_e32 v[14:15], v[72:73]
	s_waitcnt vmcnt(8)
	v_mov_b64_e32 v[66:67], v[96:97]
	v_mov_b64_e32 v[62:63], v[98:99]
	v_mov_b64_e32 v[60:61], v[100:101]
	v_mov_b64_e32 v[58:59], v[102:103]
	v_mov_b64_e32 v[54:55], v[88:89]
	v_mov_b64_e32 v[50:51], v[90:91]
	v_mov_b64_e32 v[46:47], v[92:93]
	v_mov_b64_e32 v[42:43], v[94:95]
	v_mov_b32_e32 v136, v1
	v_mov_b32_e32 v1, v17
	s_cbranch_scc1 .LBB0_57
.LBB0_53:
	s_add_i32 s14, s8, 0x200
	s_cmp_gt_i32 s14, s32
	s_cbranch_scc1 .LBB0_55
	s_ashr_i32 s15, s14, 31
	s_lshl_b64 s[4:5], s[14:15], 2
	s_add_u32 s4, s3, s4
	s_addc_u32 s5, s16, s5
	global_load_dword v17, v0, s[4:5]
	v_mad_i64_i32 v[86:87], s[4:5], s14, v227, v[68:69]
	s_lshl_b64 s[4:5], s[14:15], 12
	s_nop 0
	v_lshl_add_u64 v[96:97], v[70:71], 0, s[4:5]
	global_load_dwordx2 v[72:73], v[86:87], off
	global_load_dwordx2 v[74:75], v[86:87], off offset:512
	global_load_dwordx2 v[76:77], v[86:87], off offset:1024
	global_load_dwordx2 v[78:79], v[86:87], off offset:1536
	global_load_dwordx2 v[94:95], v[96:97], off
	global_load_dwordx2 v[92:93], v[96:97], off offset:512
	global_load_dwordx2 v[90:91], v[96:97], off offset:1024
	global_load_dwordx2 v[88:89], v[96:97], off offset:1536
	global_load_dwordx2 v[80:81], v[86:87], off offset:2048
	global_load_dwordx2 v[82:83], v[86:87], off offset:2560
	global_load_dwordx2 v[84:85], v[86:87], off offset:3072
	s_nop 0
	global_load_dwordx2 v[86:87], v[86:87], off offset:3584
	s_nop 0
	global_load_dwordx2 v[102:103], v[96:97], off offset:2048
	global_load_dwordx2 v[100:101], v[96:97], off offset:2560
	global_load_dwordx2 v[98:99], v[96:97], off offset:3072
	s_nop 0
	global_load_dwordx2 v[96:97], v[96:97], off offset:3584

; __device__ __forceinline__ void rowwise(ArgsP a, LAS unsigned char* lds, const float* xin, const bf16_t* f, float alpha, const float* gpost, const float* gnext,
;                                         bool forget, const float* w_in_L, const float* fbias, bool final) {
;     ...
;     f32x4 gp[8], gn[8];
; #pragma unroll
;     for (int j = 0; j < 8; ++j) { gp[j] = ((const f32x4*)gpost)[64 * j + lane]; gn[j] = forget ? ((const f32x4*)gnext)[64 * j + lane] : (f32x4){0.f, 0.f, 0.f, 0.f}; }
;     u32x2 hn[8], fn[8], hn2[8], fn2[8]; float rn = R2[gw], rn2 = 1.f;
;     { const u32x2* hp = (const u32x2*)(HB + (size_t)gw * LDU) + lane; const u32x2* fp = (const u32x2*)(f + (size_t)gw * DM) + lane;
; #pragma unroll
;       for (int j = 0; j < 8; ++j) { hn[j] = hp[64 * j]; fn[j] = fp[64 * j]; } }
;     if (gw + NGW < T_) { rn2 = R2[gw + NGW]; const u32x2* hp = (const u32x2*)(HB + (size_t)(gw + NGW) * LDU) + lane; const u32x2* fp = (const u32x2*)(f + (size_t)(gw + NGW) * DM) + lane;
; #pragma unroll
;       for (int j = 0; j < 8; ++j) { hn2[j] = hp[64 * j]; fn2[j] = fp[64 * j]; } }
.LBB0_58:
	s_and_b64 vcc, exec, s[12:13]
	s_cbranch_vccz .LBB0_73
	s_cmp_gt_i32 s76, 6
	s_cbranch_scc0 .LBB0_70
	s_cmp_lt_i32 s76, 8
	s_mov_b64 s[90:91], -1
	s_cbranch_scc0 .LBB0_72
	s_load_dwordx2 s[4:5], s[72:73], 0x48
	v_readlane_b32 s6, v255, 50
	v_readlane_b32 s7, v255, 51
	s_lshl_b64 s[6:7], s[6:7], 2
	s_waitcnt vmcnt(0)
	v_mov_b32_e32 v1, v219
	s_waitcnt lgkmcnt(0)
	s_add_u32 s4, s4, s6
	v_readfirstlane_b32 s3, v1
	s_addc_u32 s5, s5, s7
	s_ashr_i32 s6, s3, 6
	v_and_b32_e32 v17, 63, v1
	s_add_u32 s3, s70, 0xb280000
	v_readlane_b32 s7, v255, 62
	s_addc_u32 s14, s71, 0
	s_add_i32 s8, s6, s7
	s_waitcnt vmcnt(15)
	v_lshlrev_b32_e32 v14, 4, v17
	v_mov_b32_e32 v15, v0
	v_lshl_add_u64 v[22:23], s[4:5], 0, v[14:15]
	global_load_dwordx4 v[2:5], v14, s[4:5]
	global_load_dwordx4 v[6:9], v14, s[4:5] offset:1024
	global_load_dwordx4 v[10:13], v14, s[4:5] offset:2048
	global_load_dwordx4 v[18:21], v14, s[4:5] offset:3072
	s_movk_i32 s4, 0x1000
	s_ashr_i32 s9, s8, 31
	v_add_co_u32_e32 v14, vcc, s4, v22
	s_lshl_b64 s[4:5], s[8:9], 2
	s_add_u32 s4, s3, s4
	s_addc_u32 s5, s14, s5
	s_mul_i32 s6, s8, 0x1080
	s_mul_hi_i32 s7, s8, 0x1080
	s_add_u32 s6, s78, s6
	s_addc_u32 s7, s79, s7
	s_lshl_b64 s[12:13], s[8:9], 12
	v_addc_co_u32_e32 v15, vcc, 0, v23, vcc
	s_add_u32 s12, s80, s12
	global_load_dwordx4 v[22:25], v[14:15], off
	global_load_dwordx4 v[26:29], v[14:15], off offset:1024
	global_load_dwordx4 v[30:33], v[14:15], off offset:2048
	global_load_dwordx4 v[34:37], v[14:15], off offset:3072
	v_lshlrev_b32_e32 v70, 3, v17
	s_addc_u32 s13, s81, s13
	global_load_dword v136, v0, s[4:5]
	global_load_dwordx2 v[128:129], v70, s[6:7]
	global_load_dwordx2 v[126:127], v70, s[6:7] offset:512
	global_load_dwordx2 v[122:123], v70, s[6:7] offset:1024
	global_load_dwordx2 v[118:119], v70, s[6:7] offset:1536
	global_load_dwordx2 v[114:115], v70, s[6:7] offset:2048
	global_load_dwordx2 v[112:113], v70, s[6:7] offset:2560
	global_load_dwordx2 v[106:107], v70, s[6:7] offset:3072
	global_load_dwordx2 v[124:125], v70, s[12:13] offset:1536
	global_load_dwordx2 v[120:121], v70, s[12:13] offset:2048
	global_load_dwordx2 v[116:117], v70, s[12:13] offset:2560
	global_load_dwordx2 v[110:111], v70, s[12:13] offset:3072
	global_load_dwordx2 v[134:135], v70, s[12:13]
	global_load_dwordx2 v[132:133], v70, s[12:13] offset:512
	global_load_dwordx2 v[130:131], v70, s[12:13] offset:1024
	global_load_dwordx2 v[104:105], v70, s[6:7] offset:3584
	global_load_dwordx2 v[108:109], v70, s[12:13] offset:3584
	s_add_i32 s6, s8, 0x100
	s_cmp_gt_i32 s6, s32
	v_mov_b32_e32 v1, 1.0
	s_cbranch_scc1 .LBB0_63
	s_ashr_i32 s7, s6, 31
	s_add_u32 s4, s4, 0x400
	s_addc_u32 s5, s5, 0
	global_load_dword v1, v0, s[4:5]
	s_mul_i32 s4, s6, 0x1080
	s_mul_hi_i32 s5, s6, 0x1080
	s_add_u32 s4, s78, s4
	s_addc_u32 s5, s79, s5
	s_lshl_b64 s[6:7], s[6:7], 12
	s_add_u32 s6, s80, s6
	s_addc_u32 s7, s81, s7
	global_load_dwordx2 v[14:15], v70, s[4:5]
	global_load_dwordx2 v[42:43], v70, s[6:7]
	global_load_dwordx2 v[38:39], v70, s[4:5] offset:512
	global_load_dwordx2 v[46:47], v70, s[6:7] offset:512
	global_load_dwordx2 v[40:41], v70, s[4:5] offset:1024
	global_load_dwordx2 v[50:51], v70, s[6:7] offset:1024
	global_load_dwordx2 v[44:45], v70, s[4:5] offset:1536
	global_load_dwordx2 v[54:55], v70, s[6:7] offset:1536
	global_load_dwordx2 v[48:49], v70, s[4:5] offset:2048
	global_load_dwordx2 v[58:59], v70, s[6:7] offset:2048
	global_load_dwordx2 v[52:53], v70, s[4:5] offset:2560
	global_load_dwordx2 v[60:61], v70, s[6:7] offset:2560
	global_load_dwordx2 v[56:57], v70, s[4:5] offset:3072
	global_load_dwordx2 v[62:63], v70, s[6:7] offset:3072
	global_load_dwordx2 v[64:65], v70, s[4:5] offset:3584
	global_load_dwordx2 v[66:67], v70, s[6:7] offset:3584

; __device__ __forceinline__ unsigned cvtpk(float lo, float hi) { unsigned r; asm volatile("v_cvt_pk_bf16_f32 %0, %1, %2" : "=v"(r) : "v"(lo), "v"(hi)); return r; }
; __device__ __forceinline__ void rowwise(ArgsP a, LAS unsigned char* lds, const float* xin, const bf16_t* f, float alpha, const float* gpost, const float* gnext,
;                                         bool forget, const float* w_in_L, const float* fbias, bool final) {
;     ...
;         rn = rn2;
; #pragma unroll
;         for (int j = 0; j < 8; ++j) { hn[j] = hn2[j]; fn[j] = fn2[j]; }
;         if (r + 2 * NGW < T_) { rn2 = R2[r + 2 * NGW]; const u32x2* hp = (const u32x2*)(HB + (size_t)(r + 2 * NGW) * LDU) + lane; const u32x2* fp = (const u32x2*)(f + (size_t)(r + 2 * NGW) * DM) + lane;
; #pragma unroll
;             for (int j = 0; j < 8; ++j) { hn2[j] = hp[64 * j]; fn2[j] = fp[64 * j]; } }
;     ...
;             for (int j = 0; j < 8; ++j) { h[j] = h[j] * r2; u32x2 o; o.x = cvtpk(h[j].x, h[j].y); o.y = cvtpk(h[j].z, h[j].w); st8(hbp + 64 * j, o); }
.LBB0_65:
	s_or_b64 exec, exec, s[4:5]
	v_pk_mul_f32 v[106:107], v[106:107], v[136:137] op_sel_hi:[1,0]
	v_mad_i64_i32 v[138:139], s[4:5], s8, v227, v[68:69]
	v_pk_mul_f32 v[104:105], v[104:105], v[136:137] op_sel_hi:[1,0]
	v_cvt_pk_bf16_f32 v106, v106, v107
	s_sub_i32 s8, s12, 0x100
	v_cvt_pk_bf16_f32 v107, v104, v105
	global_store_dwordx2 v[138:139], v[106:107], off
	v_pk_mul_f32 v[106:107], v[110:111], v[136:137] op_sel_hi:[1,0]
	v_pk_mul_f32 v[104:105], v[108:109], v[136:137] op_sel_hi:[1,0]
	v_cvt_pk_bf16_f32 v106, v106, v107
	s_cmp_gt_i32 s8, s32
	v_cvt_pk_bf16_f32 v107, v104, v105
	global_store_dwordx2 v[138:139], v[106:107], off offset:512
	v_pk_mul_f32 v[106:107], v[116:117], v[136:137] op_sel_hi:[1,0]
	v_pk_mul_f32 v[104:105], v[112:113], v[136:137] op_sel_hi:[1,0]
	v_cvt_pk_bf16_f32 v106, v106, v107
	v_mov_b64_e32 v[112:113], v[52:53]
	v_cvt_pk_bf16_f32 v107, v104, v105
	global_store_dwordx2 v[138:139], v[106:107], off offset:1024
	v_pk_mul_f32 v[106:107], v[120:121], v[136:137] op_sel_hi:[1,0]
	v_pk_mul_f32 v[104:105], v[114:115], v[136:137] op_sel_hi:[1,0]
	v_cvt_pk_bf16_f32 v106, v106, v107
	v_mov_b64_e32 v[114:115], v[48:49]
	v_cvt_pk_bf16_f32 v107, v104, v105
	global_store_dwordx2 v[138:139], v[106:107], off offset:1536
	v_pk_mul_f32 v[106:107], v[118:119], v[136:137] op_sel_hi:[1,0]
	v_pk_mul_f32 v[104:105], v[124:125], v[136:137] op_sel_hi:[1,0]
	v_cvt_pk_bf16_f32 v106, v106, v107
	v_mov_b64_e32 v[118:119], v[44:45]
	v_cvt_pk_bf16_f32 v107, v104, v105
	global_store_dwordx2 v[138:139], v[106:107], off offset:2048
	v_pk_mul_f32 v[106:107], v[128:129], v[136:137] op_sel_hi:[1,0]
	v_pk_mul_f32 v[104:105], v[122:123], v[136:137] op_sel_hi:[1,0]
	v_cvt_pk_bf16_f32 v106, v106, v107
	v_mov_b64_e32 v[122:123], v[40:41]
	v_cvt_pk_bf16_f32 v107, v104, v105
	global_store_dwordx2 v[138:139], v[106:107], off offset:2560
	v_pk_mul_f32 v[106:107], v[132:133], v[136:137] op_sel_hi:[1,0]
	v_pk_mul_f32 v[104:105], v[126:127], v[136:137] op_sel_hi:[1,0]
	v_cvt_pk_bf16_f32 v106, v106, v107
	v_mov_b64_e32 v[126:127], v[38:39]
	v_cvt_pk_bf16_f32 v107, v104, v105
	global_store_dwordx2 v[138:139], v[106:107], off offset:3072
	v_pk_mul_f32 v[106:107], v[130:131], v[136:137] op_sel_hi:[1,0]
	v_pk_mul_f32 v[104:105], v[134:135], v[136:137] op_sel_hi:[1,0]
	v_cvt_pk_bf16_f32 v106, v106, v107
	v_mov_b64_e32 v[128:129], v[14:15]
	v_cvt_pk_bf16_f32 v107, v104, v105
	global_store_dwordx2 v[138:139], v[106:107], off offset:3584
	v_mov_b64_e32 v[104:105], v[64:65]
	v_mov_b64_e32 v[106:107], v[56:57]
	v_mov_b64_e32 v[108:109], v[66:67]
	v_mov_b64_e32 v[110:111], v[62:63]
	v_mov_b64_e32 v[116:117], v[60:61]
	v_mov_b64_e32 v[120:121], v[58:59]
	v_mov_b64_e32 v[124:125], v[54:55]
	v_mov_b64_e32 v[130:131], v[50:51]
	v_mov_b64_e32 v[132:133], v[46:47]
	v_mov_b64_e32 v[134:135], v[42:43]
	s_waitcnt vmcnt(12)
	v_mov_b64_e32 v[64:65], v[86:87]
	v_mov_b64_e32 v[56:57], v[84:85]
	v_mov_b64_e32 v[52:53], v[82:83]
	v_mov_b64_e32 v[48:49], v[80:81]
	v_mov_b64_e32 v[44:45], v[78:79]
	v_mov_b64_e32 v[40:41], v[76:77]
	v_mov_b64_e32 v[38:39], v[74:75]
	v_mov_b64_e32 v[14:15], v[72:73]
	s_waitcnt vmcnt(8)
	v_mov_b64_e32 v[66:67], v[96:97]
	v_mov_b64_e32 v[62:63], v[98:99]
	v_mov_b64_e32 v[60:61], v[100:101]
	v_mov_b64_e32 v[58:59], v[102:103]
	v_mov_b64_e32 v[54:55], v[88:89]
	v_mov_b64_e32 v[50:51], v[90:91]
	v_mov_b64_e32 v[46:47], v[92:93]
	v_mov_b64_e32 v[42:43], v[94:95]
	v_mov_b32_e32 v136, v1
	v_mov_b32_e32 v1, v17
	s_cbranch_scc1 .LBB0_71
.LBB0_66:
	s_add_i32 s12, s8, 0x200
	s_cmp_gt_i32 s12, s32
	s_cbranch_scc1 .LBB0_68
	s_ashr_i32 s13, s12, 31
	s_lshl_b64 s[4:5], s[12:13], 2
	s_add_u32 s4, s3, s4
	s_addc_u32 s5, s14, s5
	global_load_dword v17, v0, s[4:5]
	v_mad_i64_i32 v[86:87], s[4:5], s12, v227, v[68:69]
	s_lshl_b64 s[4:5], s[12:13], 12
	s_nop 0
	v_lshl_add_u64 v[96:97], v[70:71], 0, s[4:5]
	global_load_dwordx2 v[72:73], v[86:87], off
	global_load_dwordx2 v[74:75], v[86:87], off offset:512
	global_load_dwordx2 v[76:77], v[86:87], off offset:1024
	global_load_dwordx2 v[78:79], v[86:87], off offset:1536
	global_load_dwordx2 v[94:95], v[96:97], off
	global_load_dwordx2 v[92:93], v[96:97], off offset:512
	global_load_dwordx2 v[90:91], v[96:97], off offset:1024
	global_load_dwordx2 v[88:89], v[96:97], off offset:1536
	global_load_dwordx2 v[80:81], v[86:87], off offset:2048
	global_load_dwordx2 v[82:83], v[86:87], off offset:2560
	global_load_dwordx2 v[84:85], v[86:87], off offset:3072
	s_nop 0
	global_load_dwordx2 v[86:87], v[86:87], off offset:3584
	s_nop 0
	global_load_dwordx2 v[102:103], v[96:97], off offset:2048
	global_load_dwordx2 v[100:101], v[96:97], off offset:2560
	global_load_dwordx2 v[98:99], v[96:97], off offset:3072
	s_nop 0
	global_load_dwordx2 v[96:97], v[96:97], off offset:3584

; __device__ __forceinline__ void rowwise(ArgsP a, LAS unsigned char* lds, const float* xin, const bf16_t* f, float alpha, const float* gpost, const float* gnext,
;                                         bool forget, const float* w_in_L, const float* fbias, bool final) {
;     ...
;     f32x4 gp[8], gn[8];
; #pragma unroll
;     for (int j = 0; j < 8; ++j) { gp[j] = ((const f32x4*)gpost)[64 * j + lane]; gn[j] = forget ? ((const f32x4*)gnext)[64 * j + lane] : (f32x4){0.f, 0.f, 0.f, 0.f}; }
;     u32x2 hn[8], fn[8], hn2[8], fn2[8]; float rn = R2[gw], rn2 = 1.f;
;     { const u32x2* hp = (const u32x2*)(HB + (size_t)gw * LDU) + lane; const u32x2* fp = (const u32x2*)(f + (size_t)gw * DM) + lane;
; #pragma unroll
;       for (int j = 0; j < 8; ++j) { hn[j] = hp[64 * j]; fn[j] = fp[64 * j]; } }
;     if (gw + NGW < T_) { rn2 = R2[gw + NGW]; const u32x2* hp = (const u32x2*)(HB + (size_t)(gw + NGW) * LDU) + lane; const u32x2* fp = (const u32x2*)(f + (size_t)(gw + NGW) * DM) + lane;
; #pragma unroll
;       for (int j = 0; j < 8; ++j) { hn2[j] = hp[64 * j]; fn2[j] = fp[64 * j]; } }
.LBB0_347:
	s_or_b64 exec, exec, s[38:39]
	v_readlane_b32 s4, v255, 50
	v_readlane_b32 s5, v255, 51
	s_lshl_b64 s[4:5], s[4:5], 2
	s_waitcnt lgkmcnt(0)
	s_add_u32 s6, s36, s4
	s_addc_u32 s7, s37, s5
	v_and_b32_e32 v14, 63, v2
	s_add_u32 s4, s14, s4
	v_lshlrev_b32_e32 v15, 4, v14
	s_addc_u32 s5, s15, s5
	s_ashr_i32 s3, s3, 6
	v_or_b32_e32 v1, 0x1000, v15
	s_barrier
	s_add_u32 s23, s70, 0xb280000
	v_readlane_b32 s8, v255, 62
	global_load_dwordx4 v[2:5], v15, s[6:7]
	global_load_dwordx4 v[6:9], v15, s[6:7] offset:1024
	global_load_dwordx4 v[10:13], v15, s[4:5]
	global_load_dwordx4 v[18:21], v15, s[4:5] offset:1024
	global_load_dwordx4 v[22:25], v15, s[6:7] offset:2048
	global_load_dwordx4 v[26:29], v15, s[6:7] offset:3072
	global_load_dwordx4 v[30:33], v15, s[4:5] offset:2048
	global_load_dwordx4 v[34:37], v15, s[4:5] offset:3072
	global_load_dwordx4 v[38:41], v1, s[6:7]
	global_load_dwordx4 v[42:45], v1, s[4:5]
	v_or_b32_e32 v1, 0x1400, v15
	s_addc_u32 s35, s71, 0
	s_add_i32 s94, s3, s8
	global_load_dwordx4 v[46:49], v1, s[6:7]
	global_load_dwordx4 v[50:53], v1, s[4:5]
	v_or_b32_e32 v1, 0x1800, v15
	global_load_dwordx4 v[54:57], v1, s[6:7]
	global_load_dwordx4 v[58:61], v1, s[4:5]
	v_or_b32_e32 v1, 0x1c00, v15
	s_ashr_i32 s95, s94, 31
	global_load_dwordx4 v[62:65], v1, s[6:7]
	global_load_dwordx4 v[66:69], v1, s[4:5]
	s_lshl_b64 s[4:5], s[94:95], 2
	s_add_u32 s4, s23, s4
	s_addc_u32 s5, s35, s5
	s_mul_i32 s6, s94, 0x1080
	s_mul_hi_i32 s3, s94, 0x1080
	s_add_u32 s6, s78, s6
	s_addc_u32 s7, s79, s3
	s_lshl_b64 s[8:9], s[94:95], 12
	v_lshlrev_b32_e32 v104, 3, v14
	s_add_u32 s8, s80, s8
	global_load_dword v172, v0, s[4:5]
	s_addc_u32 s9, s81, s9
	global_load_dwordx2 v[166:167], v104, s[6:7]
	global_load_dwordx2 v[164:165], v104, s[6:7] offset:512
	global_load_dwordx2 v[160:161], v104, s[6:7] offset:1024
	global_load_dwordx2 v[154:155], v104, s[6:7] offset:1536
	global_load_dwordx2 v[170:171], v104, s[8:9]
	global_load_dwordx2 v[168:169], v104, s[8:9] offset:512
	global_load_dwordx2 v[162:163], v104, s[8:9] offset:1024
	global_load_dwordx2 v[158:159], v104, s[8:9] offset:1536
	global_load_dwordx2 v[150:151], v104, s[6:7] offset:2048
	global_load_dwordx2 v[146:147], v104, s[6:7] offset:2560
	global_load_dwordx2 v[144:145], v104, s[6:7] offset:3072
	global_load_dwordx2 v[140:141], v104, s[6:7] offset:3584
	global_load_dwordx2 v[156:157], v104, s[8:9] offset:2048
	global_load_dwordx2 v[152:153], v104, s[8:9] offset:2560
	global_load_dwordx2 v[148:149], v104, s[8:9] offset:3072
	global_load_dwordx2 v[142:143], v104, s[8:9] offset:3584
	s_add_i32 s6, s94, 0x100
	s_cmp_le_i32 s6, s32
	v_mov_b32_e32 v1, 1.0
	s_cbranch_scc0 .LBB0_349
	s_ashr_i32 s7, s6, 31
	s_add_u32 s4, s4, 0x400
	s_addc_u32 s5, s5, 0
	global_load_dword v1, v0, s[4:5]
	s_mul_i32 s4, s6, 0x1080
	s_mul_hi_i32 s3, s6, 0x1080
	s_add_u32 s4, s78, s4
	s_addc_u32 s5, s79, s3
	s_lshl_b64 s[6:7], s[6:7], 12
	s_add_u32 s6, s80, s6
	s_addc_u32 s7, s81, s7
	global_load_dwordx2 v[70:71], v104, s[4:5]
	global_load_dwordx2 v[76:77], v104, s[6:7]
	global_load_dwordx2 v[72:73], v104, s[4:5] offset:512
	global_load_dwordx2 v[80:81], v104, s[6:7] offset:512
	global_load_dwordx2 v[74:75], v104, s[4:5] offset:1024
	global_load_dwordx2 v[84:85], v104, s[6:7] offset:1024
	global_load_dwordx2 v[78:79], v104, s[4:5] offset:1536
	global_load_dwordx2 v[88:89], v104, s[6:7] offset:1536
	global_load_dwordx2 v[82:83], v104, s[4:5] offset:2048
	global_load_dwordx2 v[92:93], v104, s[6:7] offset:2048
	global_load_dwordx2 v[86:87], v104, s[4:5] offset:2560
	global_load_dwordx2 v[94:95], v104, s[6:7] offset:2560
	global_load_dwordx2 v[90:91], v104, s[4:5] offset:3072
	global_load_dwordx2 v[96:97], v104, s[6:7] offset:3072
	global_load_dwordx2 v[98:99], v104, s[4:5] offset:3584
	global_load_dwordx2 v[100:101], v104, s[6:7] offset:3584
; __device__ __forceinline__ float bf_lo(unsigned v) { return __uint_as_float(v << 16); }
; __device__ __forceinline__ float bf_hi(unsigned v) { return __uint_as_float(v & 0xffff0000u); }
; #define LAS __attribute__((address_space(3)))
; __device__ __forceinline__ float wave_sum(float v) { return wave_sum_dpp(v); }
; __device__ __forceinline__ void rowwise(ArgsP a, LAS unsigned char* lds, const float* xin, const bf16_t* f, float alpha, const float* gpost, const float* gnext,
;                                         bool forget, const float* w_in_L, const float* fbias, bool final) {
;     ...
;     if (gw + NGW < T_) { rn2 = R2[gw + NGW]; const u32x2* hp = (const u32x2*)(HB + (size_t)(gw + NGW) * LDU) + lane; const u32x2* fp = (const u32x2*)(f + (size_t)(gw + NGW) * DM) + lane;
; #pragma unroll
;       for (int j = 0; j < 8; ++j) { hn2[j] = hp[64 * j]; fn2[j] = fp[64 * j]; } }
;     for (int r = gw; r < T_; r += NGW) {
;         f32x4 h[8], fv[8];
;         u32x2* hbp = (u32x2*)(HB + (size_t)r * LDU) + lane;
;         const float ir = 1.0f / rn;
; #pragma unroll
;         for (int j = 0; j < 8; ++j) { h[j] = (f32x4){pg8::bf_lo(hn[j].x), pg8::bf_hi(hn[j].x), pg8::bf_lo(hn[j].y), pg8::bf_hi(hn[j].y)} * ir;
;                                       fv[j] = (f32x4){pg8::bf_lo(fn[j].x), pg8::bf_hi(fn[j].x), pg8::bf_lo(fn[j].y), pg8::bf_hi(fn[j].y)}; }
;         rn = rn2;
; #pragma unroll
;         for (int j = 0; j < 8; ++j) { hn[j] = hn2[j]; fn[j] = fn2[j]; }
;         if (r + 2 * NGW < T_) { rn2 = R2[r + 2 * NGW]; const u32x2* hp = (const u32x2*)(HB + (size_t)(r + 2 * NGW) * LDU) + lane; const u32x2* fp = (const u32x2*)(f + (size_t)(r + 2 * NGW) * DM) + lane;
; #pragma unroll
;             for (int j = 0; j < 8; ++j) { hn2[j] = hp[64 * j]; fn2[j] = fp[64 * j]; } }
;     ...
;                 for (int jj = 0; jj < 6; ++jj) { float s = 0.f;
; #pragma unroll
;                     for (int j = 0; j < 8; ++j) { const f32x4 w = *(const LAS f32x4*)(wf + jj * DM + 256 * j + 4 * lane); s += (h[j].x * w.x + h[j].y * w.y) + (h[j].z * w.z + h[j].w * w.w); }
;                     s = wave_sum(s); if (lane == jj) mine = s; }
;                 if (lane < 6) { const int b = r >> 11, t = r & 2047; logf_out[(size_t)(b * NH + lane) * SEQ + t] = log_sigmoidf_(mine + fbias[lane]); }
.LBB0_349:
	s_cmp_gt_i32 s94, s32
	s_cbranch_scc1 .LBB0_358
	s_add_u32 s96, s70, 0xb200000
	s_mul_i32 s4, s74, 6
	s_addc_u32 s97, s71, 0
	s_ashr_i32 s5, s4, 31
	s_lshl_b64 s[4:5], s[4:5], 2
	s_add_u32 s4, s18, s4
	v_mov_b32_e32 v105, v0
	s_addc_u32 s5, s19, s5
	v_lshlrev_b32_e32 v106, 2, v14
	v_mov_b32_e32 v107, v0
	v_lshl_add_u64 v[102:103], s[78:79], 0, v[104:105]
	v_lshl_add_u64 v[104:105], s[80:81], 0, v[104:105]
	v_cmp_eq_u32_e64 s[6:7], 0, v14
	v_cmp_gt_u32_e64 s[8:9], 6, v14
	v_lshl_add_u64 v[106:107], s[4:5], 0, v[106:107]
	v_cmp_eq_u32_e64 s[10:11], 5, v14
	v_cmp_eq_u32_e64 s[12:13], 4, v14
	v_cmp_eq_u32_e64 s[14:15], 3, v14
	v_cmp_eq_u32_e64 s[16:17], 2, v14
	v_cmp_eq_u32_e64 s[18:19], 1, v14
	v_add_u32_e32 v15, 0, v15
	s_waitcnt vmcnt(16)
	v_mov_b32_e32 v17, v1
	s_waitcnt vmcnt(1)
	v_mov_b64_e32 v[136:137], v[98:99]
	v_mov_b64_e32 v[128:129], v[90:91]
	v_mov_b64_e32 v[124:125], v[86:87]
	v_mov_b64_e32 v[120:121], v[82:83]
	v_mov_b64_e32 v[116:117], v[78:79]
	v_mov_b64_e32 v[112:113], v[74:75]
	v_mov_b64_e32 v[110:111], v[72:73]
	v_mov_b64_e32 v[108:109], v[70:71]
	s_waitcnt vmcnt(0)
	v_mov_b64_e32 v[138:139], v[100:101]
	v_mov_b64_e32 v[134:135], v[96:97]
	v_mov_b64_e32 v[132:133], v[94:95]
	v_mov_b64_e32 v[130:131], v[92:93]
	v_mov_b64_e32 v[126:127], v[88:89]
	v_mov_b64_e32 v[122:123], v[84:85]
	v_mov_b64_e32 v[118:119], v[80:81]
	v_mov_b64_e32 v[114:115], v[76:77]
	s_branch .LBB0_352
.LBB0_351:
	s_or_b64 exec, exec, s[4:5]
	s_sub_i32 s94, s36, 0x100
	s_cmp_gt_i32 s94, s32
	v_mov_b64_e32 v[140:141], v[98:99]
	v_mov_b64_e32 v[144:145], v[90:91]
	v_mov_b64_e32 v[146:147], v[86:87]
	v_mov_b64_e32 v[150:151], v[82:83]
	v_mov_b64_e32 v[154:155], v[78:79]
	v_mov_b64_e32 v[160:161], v[74:75]
	v_mov_b64_e32 v[164:165], v[72:73]
	v_mov_b64_e32 v[166:167], v[70:71]
	v_mov_b64_e32 v[142:143], v[100:101]
	v_mov_b64_e32 v[148:149], v[96:97]
	v_mov_b64_e32 v[152:153], v[94:95]
	v_mov_b64_e32 v[156:157], v[92:93]
	v_mov_b64_e32 v[158:159], v[88:89]
	v_mov_b64_e32 v[162:163], v[84:85]
	v_mov_b64_e32 v[168:169], v[80:81]
	v_mov_b64_e32 v[170:171], v[76:77]
	s_waitcnt vmcnt(9)
	v_mov_b64_e32 v[98:99], v[136:137]
	v_mov_b64_e32 v[90:91], v[128:129]
	v_mov_b64_e32 v[86:87], v[124:125]
	v_mov_b64_e32 v[82:83], v[120:121]
	v_mov_b64_e32 v[78:79], v[116:117]
	v_mov_b64_e32 v[74:75], v[112:113]
	v_mov_b64_e32 v[72:73], v[110:111]
	v_mov_b64_e32 v[70:71], v[108:109]
	s_waitcnt vmcnt(8)
	v_mov_b64_e32 v[100:101], v[138:139]
	v_mov_b64_e32 v[96:97], v[134:135]
	v_mov_b64_e32 v[94:95], v[132:133]
	v_mov_b64_e32 v[92:93], v[130:131]
	v_mov_b64_e32 v[88:89], v[126:127]
	v_mov_b64_e32 v[84:85], v[122:123]
	v_mov_b64_e32 v[80:81], v[118:119]
	v_mov_b64_e32 v[76:77], v[114:115]
	v_mov_b32_e32 v172, v1
	v_mov_b32_e32 v1, v17
	s_cbranch_scc1 .LBB0_358
.LBB0_352:
	s_add_i32 s36, s94, 0x200
	s_cmp_gt_i32 s36, s32
	s_cbranch_scc1 .LBB0_354
	s_ashr_i32 s37, s36, 31
	s_lshl_b64 s[4:5], s[36:37], 2
	s_add_u32 s4, s23, s4
	s_addc_u32 s5, s35, s5
	global_load_dword v17, v0, s[4:5]
	v_mad_i64_i32 v[136:137], s[4:5], s36, v227, v[102:103]
	s_lshl_b64 s[4:5], s[36:37], 12
	s_nop 0
	v_lshl_add_u64 v[138:139], v[104:105], 0, s[4:5]
	global_load_dwordx2 v[108:109], v[136:137], off
	global_load_dwordx2 v[114:115], v[138:139], off
	global_load_dwordx2 v[110:111], v[136:137], off offset:512
	global_load_dwordx2 v[118:119], v[138:139], off offset:512
	global_load_dwordx2 v[112:113], v[136:137], off offset:1024
	global_load_dwordx2 v[122:123], v[138:139], off offset:1024
	global_load_dwordx2 v[116:117], v[136:137], off offset:1536
	global_load_dwordx2 v[126:127], v[138:139], off offset:1536
	global_load_dwordx2 v[120:121], v[136:137], off offset:2048
	global_load_dwordx2 v[130:131], v[138:139], off offset:2048
	global_load_dwordx2 v[124:125], v[136:137], off offset:2560
	global_load_dwordx2 v[132:133], v[138:139], off offset:2560
	global_load_dwordx2 v[128:129], v[136:137], off offset:3072
	global_load_dwordx2 v[134:135], v[138:139], off offset:3072
	s_nop 0
	global_load_dwordx2 v[136:137], v[136:137], off offset:3584
	s_nop 0
	global_load_dwordx2 v[138:139], v[138:139], off offset:3584

; __device__ __forceinline__ void rowwise(ArgsP a, LAS unsigned char* lds, const float* xin, const bf16_t* f, float alpha, const float* gpost, const float* gnext,
;                                         bool forget, const float* w_in_L, const float* fbias, bool final) {
;     ...
;     f32x4 gp[8], gn[8];
; #pragma unroll
;     for (int j = 0; j < 8; ++j) { gp[j] = ((const f32x4*)gpost)[64 * j + lane]; gn[j] = forget ? ((const f32x4*)gnext)[64 * j + lane] : (f32x4){0.f, 0.f, 0.f, 0.f}; }
;     u32x2 hn[8], fn[8], hn2[8], fn2[8]; float rn = R2[gw], rn2 = 1.f;
;     { const u32x2* hp = (const u32x2*)(HB + (size_t)gw * LDU) + lane; const u32x2* fp = (const u32x2*)(f + (size_t)gw * DM) + lane;
; #pragma unroll
;       for (int j = 0; j < 8; ++j) { hn[j] = hp[64 * j]; fn[j] = fp[64 * j]; } }
;     if (gw + NGW < T_) { rn2 = R2[gw + NGW]; const u32x2* hp = (const u32x2*)(HB + (size_t)(gw + NGW) * LDU) + lane; const u32x2* fp = (const u32x2*)(f + (size_t)(gw + NGW) * DM) + lane;
; #pragma unroll
;       for (int j = 0; j < 8; ++j) { hn2[j] = hp[64 * j]; fn2[j] = fp[64 * j]; } }
.LBB0_411:
	s_andn2_b64 vcc, exec, s[84:85]
	s_mov_b32 s46, 0x108000
	s_mov_b32 s47, 0x10000
	s_mov_b32 s68, 0x16000
	s_movk_i32 s85, 0x5000
	s_mov_b32 s76, 0x3c000
	s_cbranch_vccnz .LBB0_426
	s_load_dwordx2 s[4:5], s[72:73], 0xa8
	v_readlane_b32 s6, v255, 50
	v_readlane_b32 s7, v255, 51
	s_lshl_b64 s[6:7], s[6:7], 2
	s_waitcnt vmcnt(0)
	v_mov_b32_e32 v1, v219
	s_waitcnt lgkmcnt(0)
	s_add_u32 s4, s4, s6
	v_readfirstlane_b32 s3, v1
	s_addc_u32 s5, s5, s7
	s_ashr_i32 s6, s3, 6
	v_and_b32_e32 v17, 63, v1
	s_add_u32 s3, s70, 0xb280000
	v_readlane_b32 s7, v255, 62
	s_addc_u32 s14, s71, 0
	s_add_i32 s8, s6, s7
	v_lshlrev_b32_e32 v14, 4, v17
	v_mov_b32_e32 v15, v0
	v_lshl_add_u64 v[22:23], s[4:5], 0, v[14:15]
	global_load_dwordx4 v[2:5], v14, s[4:5]
	global_load_dwordx4 v[6:9], v14, s[4:5] offset:1024
	global_load_dwordx4 v[10:13], v14, s[4:5] offset:2048
	global_load_dwordx4 v[18:21], v14, s[4:5] offset:3072
	s_movk_i32 s4, 0x1000
	s_ashr_i32 s9, s8, 31
	v_add_co_u32_e32 v34, vcc, s4, v22
	s_lshl_b64 s[4:5], s[8:9], 2
	s_add_u32 s4, s3, s4
	s_addc_u32 s5, s14, s5
	s_mul_i32 s6, s8, 0x1080
	s_mul_hi_i32 s7, s8, 0x1080
	s_add_u32 s6, s78, s6
	s_addc_u32 s7, s79, s7
	s_lshl_b64 s[10:11], s[8:9], 12
	v_addc_co_u32_e32 v35, vcc, 0, v23, vcc
	v_lshlrev_b32_e32 v104, 3, v17
	s_add_u32 s10, s80, s10
	global_load_dwordx4 v[22:25], v[34:35], off
	global_load_dwordx4 v[26:29], v[34:35], off offset:1024
	global_load_dwordx4 v[30:33], v[34:35], off offset:2048
	s_nop 0
	global_load_dwordx4 v[34:37], v[34:35], off offset:3072
	s_addc_u32 s11, s81, s11
	global_load_dword v15, v0, s[4:5]
	global_load_dwordx2 v[64:65], v104, s[6:7]
	global_load_dwordx2 v[62:63], v104, s[6:7] offset:512
	global_load_dwordx2 v[58:59], v104, s[6:7] offset:1024
	global_load_dwordx2 v[52:53], v104, s[6:7] offset:1536
	global_load_dwordx2 v[68:69], v104, s[10:11]
	global_load_dwordx2 v[66:67], v104, s[10:11] offset:512
	global_load_dwordx2 v[60:61], v104, s[10:11] offset:1024
	global_load_dwordx2 v[56:57], v104, s[10:11] offset:1536
	global_load_dwordx2 v[48:49], v104, s[6:7] offset:2048
	global_load_dwordx2 v[44:45], v104, s[6:7] offset:2560
	global_load_dwordx2 v[42:43], v104, s[6:7] offset:3072
	global_load_dwordx2 v[38:39], v104, s[6:7] offset:3584
	global_load_dwordx2 v[54:55], v104, s[10:11] offset:2048
	global_load_dwordx2 v[50:51], v104, s[10:11] offset:2560
	global_load_dwordx2 v[46:47], v104, s[10:11] offset:3072
	global_load_dwordx2 v[40:41], v104, s[10:11] offset:3584
	s_add_i32 s6, s8, 0x100
	s_cmp_gt_i32 s6, s32
	v_mov_b32_e32 v1, 1.0
	s_cbranch_scc1 .LBB0_414
	s_ashr_i32 s7, s6, 31
	s_add_u32 s4, s4, 0x400
	s_addc_u32 s5, s5, 0
	global_load_dword v1, v0, s[4:5]
	s_mul_i32 s4, s6, 0x1080
	s_mul_hi_i32 s5, s6, 0x1080
	s_add_u32 s4, s78, s4
	s_addc_u32 s5, s79, s5
	s_lshl_b64 s[6:7], s[6:7], 12
	s_add_u32 s6, s80, s6
	s_addc_u32 s7, s81, s7
	global_load_dwordx2 v[70:71], v104, s[4:5]
	global_load_dwordx2 v[76:77], v104, s[6:7]
	global_load_dwordx2 v[72:73], v104, s[4:5] offset:512
	global_load_dwordx2 v[80:81], v104, s[6:7] offset:512
	global_load_dwordx2 v[74:75], v104, s[4:5] offset:1024
	global_load_dwordx2 v[84:85], v104, s[6:7] offset:1024
	global_load_dwordx2 v[78:79], v104, s[4:5] offset:1536
	global_load_dwordx2 v[88:89], v104, s[6:7] offset:1536
	global_load_dwordx2 v[82:83], v104, s[4:5] offset:2048
	global_load_dwordx2 v[92:93], v104, s[6:7] offset:2048
	global_load_dwordx2 v[86:87], v104, s[4:5] offset:2560
	global_load_dwordx2 v[94:95], v104, s[6:7] offset:2560
	global_load_dwordx2 v[90:91], v104, s[4:5] offset:3072
	global_load_dwordx2 v[96:97], v104, s[6:7] offset:3072
	global_load_dwordx2 v[98:99], v104, s[4:5] offset:3584
	global_load_dwordx2 v[100:101], v104, s[6:7] offset:3584
; __device__ __forceinline__ float bf_lo(unsigned v) { return __uint_as_float(v << 16); }
; __device__ __forceinline__ float bf_hi(unsigned v) { return __uint_as_float(v & 0xffff0000u); }
; __device__ __forceinline__ void rowwise(ArgsP a, LAS unsigned char* lds, const float* xin, const bf16_t* f, float alpha, const float* gpost, const float* gnext,
;                                         bool forget, const float* w_in_L, const float* fbias, bool final) {
;     ...
;     for (int r = gw; r < T_; r += NGW) {
;         f32x4 h[8], fv[8];
;         u32x2* hbp = (u32x2*)(HB + (size_t)r * LDU) + lane;
;         const float ir = 1.0f / rn;
; #pragma unroll
;         for (int j = 0; j < 8; ++j) { h[j] = (f32x4){pg8::bf_lo(hn[j].x), pg8::bf_hi(hn[j].x), pg8::bf_lo(hn[j].y), pg8::bf_hi(hn[j].y)} * ir;
;                                       fv[j] = (f32x4){pg8::bf_lo(fn[j].x), pg8::bf_hi(fn[j].x), pg8::bf_lo(fn[j].y), pg8::bf_hi(fn[j].y)}; }
;         rn = rn2;
; #pragma unroll
;         for (int j = 0; j < 8; ++j) { hn[j] = hn2[j]; fn[j] = fn2[j]; }
;         if (r + 2 * NGW < T_) { rn2 = R2[r + 2 * NGW]; const u32x2* hp = (const u32x2*)(HB + (size_t)(r + 2 * NGW) * LDU) + lane; const u32x2* fp = (const u32x2*)(f + (size_t)(r + 2 * NGW) * DM) + lane;
; #pragma unroll
;             for (int j = 0; j < 8; ++j) { hn2[j] = hp[64 * j]; fn2[j] = fp[64 * j]; } }
;     ...
;         if (final) {
.LBB0_414:
	s_cmp_gt_i32 s8, s32
	s_cbranch_scc1 .LBB0_425
	s_add_i32 s4, s29, -14
	v_mov_b32_e32 v105, v0
	s_cmp_gt_u32 s4, 13
	v_lshl_add_u64 v[102:103], s[78:79], 0, v[104:105]
	v_lshl_add_u64 v[104:105], s[80:81], 0, v[104:105]
	s_cselect_b64 s[10:11], -1, 0
	v_cmp_eq_u32_e64 s[6:7], 0, v17
	s_waitcnt vmcnt(16)
	v_mov_b32_e32 v17, v1
	s_waitcnt vmcnt(1)
	v_mov_b64_e32 v[134:135], v[98:99]
	v_mov_b64_e32 v[126:127], v[90:91]
	v_mov_b64_e32 v[122:123], v[86:87]
	v_mov_b64_e32 v[118:119], v[82:83]
	v_mov_b64_e32 v[114:115], v[78:79]
	v_mov_b64_e32 v[110:111], v[74:75]
	v_mov_b64_e32 v[108:109], v[72:73]
	v_mov_b64_e32 v[106:107], v[70:71]
	s_waitcnt vmcnt(0)
	v_mov_b64_e32 v[136:137], v[100:101]
	v_mov_b64_e32 v[132:133], v[96:97]
	v_mov_b64_e32 v[130:131], v[94:95]
	v_mov_b64_e32 v[128:129], v[92:93]
	v_mov_b64_e32 v[124:125], v[88:89]
	v_mov_b64_e32 v[120:121], v[84:85]
	v_mov_b64_e32 v[116:117], v[80:81]
	v_mov_b64_e32 v[112:113], v[76:77]
	s_branch .LBB0_417
.LBB0_416:
	s_sub_i32 s8, s12, 0x100
	s_cmp_gt_i32 s8, s32
	v_mov_b64_e32 v[38:39], v[98:99]
	v_mov_b64_e32 v[42:43], v[90:91]
	v_mov_b64_e32 v[44:45], v[86:87]
	v_mov_b64_e32 v[48:49], v[82:83]
	v_mov_b64_e32 v[52:53], v[78:79]
	v_mov_b64_e32 v[58:59], v[74:75]
	v_mov_b64_e32 v[62:63], v[72:73]
	v_mov_b64_e32 v[64:65], v[70:71]
	v_mov_b64_e32 v[40:41], v[100:101]
	v_mov_b64_e32 v[46:47], v[96:97]
	v_mov_b64_e32 v[50:51], v[94:95]
	v_mov_b64_e32 v[54:55], v[92:93]
	v_mov_b64_e32 v[56:57], v[88:89]
	v_mov_b64_e32 v[60:61], v[84:85]
	v_mov_b64_e32 v[66:67], v[80:81]
	v_mov_b64_e32 v[68:69], v[76:77]
	s_waitcnt vmcnt(1)
	v_mov_b64_e32 v[98:99], v[134:135]
	v_mov_b64_e32 v[90:91], v[126:127]
	v_mov_b64_e32 v[86:87], v[122:123]
	v_mov_b64_e32 v[82:83], v[118:119]
	v_mov_b64_e32 v[78:79], v[114:115]
	v_mov_b64_e32 v[74:75], v[110:111]
	v_mov_b64_e32 v[72:73], v[108:109]
	v_mov_b64_e32 v[70:71], v[106:107]
	s_waitcnt vmcnt(0)
	v_mov_b64_e32 v[100:101], v[136:137]
	v_mov_b64_e32 v[96:97], v[132:133]
	v_mov_b64_e32 v[94:95], v[130:131]
	v_mov_b64_e32 v[92:93], v[128:129]
	v_mov_b64_e32 v[88:89], v[124:125]
	v_mov_b64_e32 v[84:85], v[120:121]
	v_mov_b64_e32 v[80:81], v[116:117]
	v_mov_b64_e32 v[76:77], v[112:113]
	v_mov_b32_e32 v15, v1
	v_mov_b32_e32 v1, v17
	s_cbranch_scc1 .LBB0_425
.LBB0_417:
	s_add_i32 s12, s8, 0x200
	s_cmp_gt_i32 s12, s32
	s_cbranch_scc1 .LBB0_419
	s_ashr_i32 s13, s12, 31
	s_lshl_b64 s[4:5], s[12:13], 2
	s_add_u32 s4, s3, s4
	s_addc_u32 s5, s14, s5
	global_load_dword v17, v0, s[4:5]
	v_mad_i64_i32 v[134:135], s[4:5], s12, v227, v[102:103]
	s_lshl_b64 s[4:5], s[12:13], 12
	s_nop 0
	v_lshl_add_u64 v[136:137], v[104:105], 0, s[4:5]
	global_load_dwordx2 v[106:107], v[134:135], off
	global_load_dwordx2 v[112:113], v[136:137], off
	global_load_dwordx2 v[108:109], v[134:135], off offset:512
	global_load_dwordx2 v[116:117], v[136:137], off offset:512
	global_load_dwordx2 v[110:111], v[134:135], off offset:1024
	global_load_dwordx2 v[120:121], v[136:137], off offset:1024
	global_load_dwordx2 v[114:115], v[134:135], off offset:1536
	global_load_dwordx2 v[124:125], v[136:137], off offset:1536
	global_load_dwordx2 v[118:119], v[134:135], off offset:2048
	global_load_dwordx2 v[128:129], v[136:137], off offset:2048
	global_load_dwordx2 v[122:123], v[134:135], off offset:2560
	global_load_dwordx2 v[130:131], v[136:137], off offset:2560
	global_load_dwordx2 v[126:127], v[134:135], off offset:3072
	global_load_dwordx2 v[132:133], v[136:137], off offset:3072
	s_nop 0
	global_load_dwordx2 v[134:135], v[134:135], off offset:3584
	s_nop 0
	global_load_dwordx2 v[136:137], v[136:137], off offset:3584
